# MoBA loop half-step stagger: waves 4-7 s_sleep 9 at each step start (lockstep single-barrier loop), on top of transition trims + LUT batching; placement kept mod 32
# baseline (speedup 1.0000x reference)
.LBB0_271:
	v_writelane_b32 v255, s18, 56
	s_nop 1
	v_writelane_b32 v255, s19, 57
	s_or_b64 exec, exec, s[0:1]
	v_readlane_b32 s0, v255, 23
	v_readlane_b32 s1, v255, 24
	s_xor_b64 s[80:81], s[0:1], -1
	s_and_b64 s[0:1], s[0:1], exec
	s_movk_i32 s0, 0x180
	v_readlane_b32 s6, v255, 26
	v_readlane_b32 s2, v255, 21
	s_cselect_b32 s16, s0, 0x300
	v_readlane_b32 s7, v255, 27
	v_readlane_b32 s3, v255, 22
	s_lshl_b32 s2, s2, 7
	s_add_i32 s17, s16, 0x80
	s_lshl_b64 s[0:1], s[6:7], 21
	s_ashr_i32 s3, s2, 31
	s_lshl_b64 s[4:5], s[6:7], 2
	s_waitcnt lgkmcnt(0)
	s_add_u32 s82, s74, s4
	v_readlane_b32 s4, v255, 25
	s_addc_u32 s83, s75, s5
	s_lshl_b32 s4, s4, 1
	s_add_u32 s84, s74, s4
	s_addc_u32 s85, s75, 0
	s_add_u32 s0, s74, s0
	s_addc_u32 s1, s75, s1
	s_add_u32 s86, s0, 0x20d00000
	s_addc_u32 s87, s1, 0
	s_add_u32 s88, s74, 0x21500000
	s_addc_u32 s89, s75, 0
	s_add_u32 s90, s74, 0x26500000
	s_addc_u32 s91, s75, 0
	s_add_u32 s92, s74, 0x29500000
	s_mov_b32 s0, s6
	s_addc_u32 s93, s75, 0
	s_ashr_i32 s7, s6, 31
	v_writelane_b32 v255, s0, 26
	s_mov_b64 s[96:97], 0
	s_waitcnt vmcnt(0)
	v_writelane_b32 v255, s1, 27
	s_lshl_b64 s[0:1], s[6:7], 2
	s_add_u32 s94, s74, s0
	s_addc_u32 s95, s75, s1
	s_add_u32 s0, s74, 0x30d00000
	s_addc_u32 s1, s75, 0
	v_writelane_b32 v255, s0, 54
	s_barrier
	s_nop 0
	v_writelane_b32 v255, s1, 55
	s_lshl_b64 s[0:1], s[2:3], 2
	v_writelane_b32 v255, s0, 58
	s_nop 1
	v_writelane_b32 v255, s1, 59
	v_readfirstlane_b32 s98, v232
	s_cmpk_ge_u32 s98, 0x100
	s_cselect_b32 s98, 1, 0
	s_nop 0
	s_nop 0
	s_nop 0
	s_nop 0
	s_nop 0
	s_branch .LBB0_275

.LBB0_467:
	s_cmp_eq_u32 s98, 0
	s_cbranch_scc1 .Lmoba_nosleep
	s_sleep 9
.Lmoba_nosleep:
	s_nop 0
	s_nop 0
	s_nop 0
	s_nop 0
	s_nop 0
	s_add_i32 s0, s18, 35
	v_mov_b32_e32 v1, v77
	v_cmp_ge_i32_e64 s[40:41], s0, v184
	v_cmp_lt_i32_e32 vcc, s0, v184
	s_and_saveexec_b64 s[0:1], vcc
	s_cbranch_execz .LBB0_469
	s_add_i32 s12, s26, s19
	v_lshl_add_u64 v[66:67], v[172:173], 0, v[170:171]
	s_mov_b32 m0, s12
	s_nop 0
	global_load_lds_dwordx4 v[66:67], off
	v_lshl_add_u64 v[66:67], v[172:173], 0, v[174:175]
	s_add_i32 m0, s12, 0x400
	s_nop 0
	global_load_lds_dwordx4 v[66:67], off
	s_add_i32 m0, s12, 0x4000
	v_lshl_add_u64 v[66:67], v[172:173], 0, v[176:177]
	global_load_lds_dwordx4 v[66:67], off
	v_lshl_add_u64 v[66:67], v[172:173], 0, v[178:179]
	s_add_i32 m0, s12, 0x4400
	s_nop 0
	global_load_lds_dwordx4 v[66:67], off

	.amdhsa_kernel _Z3fwd4Args
		.amdhsa_group_segment_fixed_size 0
		.amdhsa_private_segment_fixed_size 0
		.amdhsa_kernarg_size 416
		.amdhsa_user_sgpr_count 2
		.amdhsa_user_sgpr_dispatch_ptr 0
		.amdhsa_user_sgpr_queue_ptr 0
		.amdhsa_user_sgpr_kernarg_segment_ptr 1
		.amdhsa_user_sgpr_dispatch_id 0
		.amdhsa_user_sgpr_kernarg_preload_length 0
		.amdhsa_user_sgpr_kernarg_preload_offset 0
		.amdhsa_user_sgpr_private_segment_size 0
		.amdhsa_uses_dynamic_stack 0
		.amdhsa_enable_private_segment 0
		.amdhsa_system_sgpr_workgroup_id_x 1
		.amdhsa_system_sgpr_workgroup_id_y 0
		.amdhsa_system_sgpr_workgroup_id_z 0
		.amdhsa_system_sgpr_workgroup_info 0
		.amdhsa_system_vgpr_workitem_id 2
		.amdhsa_next_free_vgpr 256
		.amdhsa_next_free_sgpr 99
		.amdhsa_accum_offset 256
		.amdhsa_reserve_vcc 1
		.amdhsa_float_round_mode_32 0
		.amdhsa_float_round_mode_16_64 0
		.amdhsa_float_denorm_mode_32 3
		.amdhsa_float_denorm_mode_16_64 3
		.amdhsa_dx10_clamp 1
		.amdhsa_ieee_mode 1
		.amdhsa_fp16_overflow 0
		.amdhsa_tg_split 0
		.amdhsa_exception_fp_ieee_invalid_op 0
		.amdhsa_exception_fp_denorm_src 0
		.amdhsa_exception_fp_ieee_div_zero 0
		.amdhsa_exception_fp_ieee_overflow 0
		.amdhsa_exception_fp_ieee_underflow 0
		.amdhsa_exception_fp_ieee_inexact 0
		.amdhsa_exception_int_div_zero 0
	.end_amdhsa_kernel

amdhsa.kernels:
  - .agpr_count:     0
    .args:
      - .offset:         0
        .size:           160
        .value_kind:     by_value
      - .offset:         160
        .size:           4
        .value_kind:     hidden_block_count_x
      - .offset:         164
        .size:           4
        .value_kind:     hidden_block_count_y
      - .offset:         168
        .size:           4
        .value_kind:     hidden_block_count_z
      - .offset:         172
        .size:           2
        .value_kind:     hidden_group_size_x
      - .offset:         174
        .size:           2
        .value_kind:     hidden_group_size_y
      - .offset:         176
        .size:           2
        .value_kind:     hidden_group_size_z
      - .offset:         178
        .size:           2
        .value_kind:     hidden_remainder_x
      - .offset:         180
        .size:           2
        .value_kind:     hidden_remainder_y
      - .offset:         182
        .size:           2
        .value_kind:     hidden_remainder_z
      - .offset:         200
        .size:           8
        .value_kind:     hidden_global_offset_x
      - .offset:         208
        .size:           8
        .value_kind:     hidden_global_offset_y
      - .offset:         216
        .size:           8
        .value_kind:     hidden_global_offset_z
      - .offset:         224
        .size:           2
        .value_kind:     hidden_grid_dims
      - .offset:         248
        .size:           8
        .value_kind:     hidden_multigrid_sync_arg
      - .offset:         280
        .size:           4
        .value_kind:     hidden_dynamic_lds_size
    .group_segment_fixed_size: 0
    .kernarg_segment_align: 8
    .kernarg_segment_size: 416
    .language:       OpenCL C
    .language_version:
      - 2
      - 0
    .max_flat_workgroup_size: 512
    .name:           _Z3fwd4Args
    .private_segment_fixed_size: 0
    .sgpr_count:     105
    .sgpr_spill_count: 199
    .symbol:         _Z3fwd4Args.kd
    .uniform_work_group_size: 1
    .uses_dynamic_stack: false
    .vgpr_count:     256
    .vgpr_spill_count: 0
    .wavefront_size: 64
